# attention unit heads (both attention kinds): first K/V tile and mask loads issued right behind the Q loads, Q arrival covered by the existing counted waits
# baseline (speedup 1.0000x reference)
.LBB0_36:
	s_lshl_b32 s1, s17, 20
	s_and_b32 s10, s1, 0x7800000
	s_lshl_b32 s1, s17, 5
	s_lshr_b32 s0, s17, 3
	s_and_b32 s2, s1, 0xf00
	s_ashr_i32 s1, s17, 3
	s_and_b32 s0, s0, 16
	s_andn2_b32 s1, s1, 31
	s_or_b32 s0, s0, s1
	s_and_b32 s8, s17, 7
	s_ashr_i32 s0, s0, 4
	s_and_b32 s1, s17, 0x100
	s_xor_b32 s9, s8, 7
	s_cmp_eq_u32 s1, 0
	s_cselect_b32 s11, s8, s9
	s_lshl_b32 s13, s11, 8
	s_add_i32 s12, s13, s38
	s_ashr_i32 s1, s0, 31
	s_lshl_b64 s[8:9], s[0:1], 11
	s_ashr_i32 s26, s12, 31
	s_add_u32 s8, s8, s12
	s_addc_u32 s9, s9, s26
	s_lshl_b64 s[26:27], s[8:9], 11
	s_lshl_b64 s[8:9], s[8:9], 12
	s_add_u32 s8, s21, s8
	s_addc_u32 s9, s30, s9
	s_lshl_b32 s28, s17, 4
	s_and_b32 s41, s28, 0x780
	s_lshl_b32 s28, s41, 1
	s_add_u32 s8, s8, s28
	s_addc_u32 s9, s9, 0
	v_lshl_add_u64 v[2:3], s[8:9], 0, v[160:161]
	v_lshl_add_u64 v[2:3], v[146:147], 1, v[2:3]
	global_load_dwordx4 v[98:101], v[2:3], off
	global_load_dwordx4 v[102:105], v[2:3], off offset:32
	global_load_dwordx4 v[106:109], v[2:3], off offset:64
	global_load_dwordx4 v[110:113], v[2:3], off offset:96
	global_load_dwordx4 v[114:117], v[2:3], off offset:128
	global_load_dwordx4 v[118:121], v[2:3], off offset:160
	global_load_dwordx4 v[122:125], v[2:3], off offset:192
	global_load_dwordx4 v[126:129], v[2:3], off offset:224
	s_lshl_b64 s[8:9], s[0:1], 23
	s_add_u32 s42, s31, s8
	s_addc_u32 s43, s33, s9
	s_add_u32 s42, s42, s28
	s_addc_u32 s43, s43, 0
	s_lshl_b32 s28, s41, 16
	s_add_u32 s28, s34, s28
	s_addc_u32 s45, s35, 0
	s_lshl_b64 s[0:1], s[0:1], 12
	s_add_u32 s44, s28, s0
	s_addc_u32 s45, s45, s1
	s_or_b32 s46, s13, 0xc0
	v_add_u32_e32 v2, s46, v179
	v_ashrrev_i32_e32 v3, 31, v2
	v_lshlrev_b64 v[2:3], 12, v[2:3]
	v_lshl_add_u64 v[2:3], s[42:43], 0, v[2:3]
	s_mov_b32 s29, s3
	v_lshl_add_u64 v[4:5], s[44:45], 0, v[148:149]
	s_lshl_b32 s28, s46, 1
	v_lshl_add_u64 v[6:7], s[44:45], 0, v[150:151]
	v_lshl_add_u64 v[2:3], v[2:3], 0, v[162:163]
	v_lshl_add_u64 v[4:5], v[4:5], 0, s[28:29]
	v_lshl_add_u64 v[6:7], v[6:7], 0, s[28:29]
	v_add_co_u32_e32 v8, vcc, s57, v2
	v_lshl_add_u64 v[4:5], v[4:5], 0, v[164:165]
	v_lshl_add_u64 v[6:7], v[6:7], 0, v[164:165]
	v_addc_co_u32_e32 v9, vcc, 0, v3, vcc
	v_add_u32_e32 v16, s13, v193
	v_add_u32_e32 v66, s13, v194
	v_ashrrev_i32_e32 v17, 31, v16
	v_ashrrev_i32_e32 v67, 31, v66
	v_lshlrev_b64 v[16:17], 12, v[16:17]
	v_lshlrev_b64 v[66:67], 12, v[66:67]
	v_lshl_add_u64 v[68:69], v[154:155], 0, s[8:9]
	v_lshl_add_u64 v[16:17], v[68:69], 0, v[16:17]
	v_lshl_add_u64 v[66:67], v[68:69], 0, v[66:67]
	s_lshl_b32 s8, s11, 2
	s_lshl_b32 s9, s11, 9
	v_mov_b32_e32 v14, v1
	v_mov_b32_e32 v15, v1
	v_lshl_add_u64 v[166:167], v[16:17], 0, s[2:3]
	v_lshl_add_u64 v[168:169], v[66:67], 0, s[2:3]
	s_or_b32 s2, s12, 31
	s_add_i32 s43, s8, 4
	s_or_b32 s0, s0, s9
	v_mov_b32_e32 v0, v1
	v_mov_b32_e32 v10, v1
	v_mov_b32_e32 v11, v1
	v_mov_b32_e32 v12, v1
	v_mov_b32_e32 v13, v1
	s_add_u32 s0, s0, s10
	s_addc_u32 s1, s1, 0
	s_mov_b32 s42, 1
	v_mov_b32_e32 v172, 0
	v_mov_b32_e32 v159, v192
	v_mov_b32_e32 v198, s46
	s_xor_b32 s44, s8, -4
	v_lshl_add_u64 v[170:171], s[0:1], 0, v[152:153]
	global_load_dwordx4 v[130:133], v[2:3], off
	global_load_dwordx4 v[134:137], v[8:9], off
	global_load_dwordx4 v[138:141], v[4:5], off
	global_load_dwordx4 v[142:145], v[6:7], off
	v_mov_b32_e32 v2, v1
	v_mov_b32_e32 v3, v1
	v_mov_b32_e32 v4, v1
	v_mov_b32_e32 v5, v1
	v_mov_b32_e32 v6, v1
	v_mov_b32_e32 v7, v1
	v_mov_b32_e32 v8, v1
	v_mov_b32_e32 v9, v1
	v_mov_b64_e32 v[64:65], v[14:15]
	v_mov_b64_e32 v[48:49], v[14:15]
	v_mov_b64_e32 v[32:33], v[14:15]
	v_mov_b64_e32 v[62:63], v[12:13]
	v_mov_b64_e32 v[60:61], v[10:11]
	v_mov_b64_e32 v[58:59], v[8:9]
	v_mov_b64_e32 v[56:57], v[6:7]
	v_mov_b64_e32 v[54:55], v[4:5]
	v_mov_b64_e32 v[52:53], v[2:3]
	v_mov_b64_e32 v[50:51], v[0:1]
	v_mov_b64_e32 v[46:47], v[12:13]
	v_mov_b64_e32 v[44:45], v[10:11]
	v_mov_b64_e32 v[42:43], v[8:9]
	v_mov_b64_e32 v[40:41], v[6:7]
	v_mov_b64_e32 v[38:39], v[4:5]
	v_mov_b64_e32 v[36:37], v[2:3]
	v_mov_b64_e32 v[34:35], v[0:1]
	v_mov_b64_e32 v[30:31], v[12:13]
	v_mov_b64_e32 v[28:29], v[10:11]
	v_mov_b64_e32 v[26:27], v[8:9]
	v_mov_b64_e32 v[24:25], v[6:7]
	v_mov_b64_e32 v[22:23], v[4:5]
	v_mov_b64_e32 v[20:21], v[2:3]
	v_mov_b64_e32 v[18:19], v[0:1]
	v_mov_b64_e32 v[16:17], v[14:15]
	v_mov_b64_e32 v[14:15], v[12:13]
	v_mov_b64_e32 v[12:13], v[10:11]
	v_mov_b64_e32 v[10:11], v[8:9]
	v_mov_b64_e32 v[8:9], v[6:7]
	v_mov_b64_e32 v[6:7], v[4:5]
	v_mov_b64_e32 v[4:5], v[2:3]
	v_mov_b64_e32 v[2:3], v[0:1]
	s_waitcnt vmcnt(3)
	ds_write_b128 v195, v[130:133]
	s_waitcnt vmcnt(2)
	ds_write_b128 v195, v[134:137] offset:8704
	s_waitcnt vmcnt(1)
	ds_write2_b64 v196, v[138:139], v[140:141] offset0:128 offset1:130
	s_waitcnt vmcnt(0)
	ds_write2_b64 v197, v[142:143], v[144:145] offset1:2
	s_waitcnt lgkmcnt(0)
	s_barrier
	s_branch .LBB0_38

.LBB0_58:
	s_lshr_b32 s45, s2, 5
	s_ashr_i32 s1, s2, 5
	s_and_b32 s0, s45, 4
	s_and_b32 s1, s1, -8
	s_or_b32 s0, s0, s1
	s_and_b32 s1, s2, 31
	s_ashr_i32 s8, s0, 2
	s_bfe_u32 s44, s2, 0x20005
	s_and_b32 s0, s2, 0x100
	s_xor_b32 s9, s1, 31
	s_cmp_eq_u32 s0, 0
	s_cselect_b32 s43, s1, s9
	s_lshl_b32 s0, s43, 6
	s_ashr_i32 s9, s8, 31
	s_or_b32 s26, s0, s39
	s_lshl_b64 s[0:1], s[8:9], 11
	s_or_b32 s0, s0, s26
	s_lshl_b64 s[26:27], s[0:1], 12
	s_add_u32 s28, s17, s26
	s_addc_u32 s29, s21, s27
	s_lshl_b32 s26, s44, 9
	s_add_i32 s26, s26, s40
	s_ashr_i32 s27, s26, 31
	s_lshl_b64 s[26:27], s[26:27], 1
	s_add_u32 s28, s28, s26
	s_addc_u32 s29, s29, s27
	v_mov_b32_e32 v193, v1
	v_lshl_add_u64 v[2:3], s[28:29], 0, v[192:193]
	v_lshl_add_u64 v[2:3], v[164:165], 1, v[2:3]
	global_load_dwordx4 v[98:101], v[2:3], off
	global_load_dwordx4 v[102:105], v[2:3], off offset:32
	global_load_dwordx4 v[106:109], v[2:3], off offset:64
	global_load_dwordx4 v[110:113], v[2:3], off offset:96
	global_load_dwordx4 v[114:117], v[2:3], off offset:128
	global_load_dwordx4 v[118:121], v[2:3], off offset:160
	global_load_dwordx4 v[122:125], v[2:3], off offset:192
	global_load_dwordx4 v[126:129], v[2:3], off offset:224
	s_lshl_b64 s[30:31], s[8:9], 21
	s_add_u32 s28, s33, s30
	s_addc_u32 s29, s34, s31
	s_lshl_b32 s46, s44, 8
	s_add_u32 s28, s28, s46
	s_addc_u32 s29, s29, 0
	s_lshl_b32 s44, s44, 23
	s_add_u32 s44, s35, s44
	s_addc_u32 s47, s36, 0
	s_lshl_b64 s[8:9], s[8:9], 12
	s_add_u32 s46, s44, s8
	v_mov_b32_e32 v3, s1
	v_or_b32_e32 v2, s0, v162
	v_lshl_add_u64 v[4:5], s[28:29], 0, v[166:167]
	v_lshl_add_u64 v[6:7], s[28:29], 0, v[168:169]
	s_addc_u32 s47, s47, s9
	v_mov_b32_e32 v195, v1
	v_lshlrev_b64 v[2:3], 8, v[2:3]
	v_lshl_add_u64 v[8:9], v[4:5], 0, v[0:1]
	v_lshl_add_u64 v[10:11], v[6:7], 0, v[0:1]
	v_lshl_add_u64 v[4:5], s[46:47], 0, v[170:171]
	v_lshl_add_u64 v[6:7], s[46:47], 0, v[172:173]
	v_lshl_add_u64 v[2:3], s[12:13], 0, v[2:3]
	v_lshl_add_u64 v[4:5], v[4:5], 0, v[194:195]
	v_lshl_add_u64 v[6:7], v[6:7], 0, v[194:195]
	s_cmp_eq_u32 s43, 0
	global_load_dwordx4 v[130:133], v[8:9], off
	global_load_dwordx4 v[134:137], v[10:11], off
	global_load_dwordx4 v[138:141], v[4:5], off
	global_load_dwordx4 v[142:145], v[6:7], off
	global_load_dwordx2 v[202:203], v[2:3], off
	v_add_u32_e32 v8, 0x4000, v214
	v_add_u32_e32 v9, 0x6800, v214
	s_waitcnt vmcnt(4)
	ds_write_b128 v213, v[130:133]
	s_waitcnt vmcnt(3)
	ds_write_b128 v213, v[134:137] offset:8704
	s_waitcnt vmcnt(2)
	ds_write2_b64 v8, v[138:139], v[140:141] offset0:128 offset1:130
	s_waitcnt vmcnt(1)
	ds_write2_b64 v9, v[142:143], v[144:145] offset1:2
	s_cbranch_scc1 .LBB0_60
	v_lshl_add_u64 v[10:11], s[28:29], 0, v[182:183]
	v_lshl_add_u64 v[8:9], s[28:29], 0, v[184:185]
	v_lshl_add_u64 v[10:11], v[10:11], 0, v[0:1]
	v_lshl_add_u64 v[8:9], v[8:9], 0, v[0:1]
	global_load_dwordx4 v[130:133], v[10:11], off
	global_load_dwordx4 v[134:137], v[8:9], off
	global_load_dwordx4 v[138:141], v[4:5], off offset:128
	global_load_dwordx4 v[142:145], v[6:7], off offset:128
